# v106: v99 with the exp2 of S1[0..7] moved from the second half of a plain differential tile into the gaps of P2-P4 (fresh registers)
# baseline (speedup 1.0000x reference)
; #define ATT_PV(v_, p_) do { const bf16x8 pf_ = __builtin_bit_cast(bf16x8, (p_)); _Pragma("unroll") for (int d = 0; d < 4; ++d) { \
;         const bf16x8 vf_ = __builtin_shufflevector((v_)[2 * d], (v_)[2 * d + 1], 0, 1, 2, 3, 4, 5, 6, 7); O[d] = MFMA32(vf_, pf_, O[d]); } } while (0)
; template <bool ONLINE, int NO>
; __device__ __forceinline__ void softmax_tile(f32x16 (&s)[2], float& m, float& l, f32x16 (&O)[NO], u32x4 (&pk)[4]) {
;     ...
;     float ps = 0.f;
; #pragma unroll
;     for (int blk = 0; blk < 2; ++blk)
; #pragma unroll
;         for (int i = 0; i < 16; ++i) { const float p = __builtin_amdgcn_exp2f(ONLINE ? (s[blk][i] - mn) : s[blk][i]); ps += p; s[blk][i] = p; }
;     l += ps;
; #pragma unroll
;     for (int blk = 0; blk < 2; ++blk)
; #pragma unroll
;         for (int sh = 0; sh < 2; ++sh) { u32x4 pw;
;             pw.x = cvt_pk_bf16(s[blk][8 * sh], s[blk][8 * sh + 1]); pw.y = cvt_pk_bf16(s[blk][8 * sh + 2], s[blk][8 * sh + 3]);
;             pw.z = cvt_pk_bf16(s[blk][8 * sh + 4], s[blk][8 * sh + 5]); pw.w = cvt_pk_bf16(s[blk][8 * sh + 6], s[blk][8 * sh + 7]); pk[2 * blk + sh] = pw; }
; template <int MODE>
; __device__ __forceinline__ void attn_unit(const Params& P, LAS unsigned char* lds, const int b, const int h, const int qb) {
;     ...
;             softmax_tile<ONLINE, 4>(s, m1, l1, O, pk1);
;             if constexpr (MODE == 1) {
;                 v_issue<2>(vc, vaddr); v_wait<15>(va); ATT_PV(va, pk1[0]); v_issue<3>(vd, vaddr); v_wait<15>(vb); ATT_PV(vb, pk1[1]); v_wait<8>(vc); ATT_PV(vc, pk1[2]); v_wait<0>(vd); ATT_PV(vd, pk1[3]);
.LBB0_483:
	s_barrier
	s_cmpk_lt_u32 s58, 0x100
	s_cbranch_scc1 .LBB0_485
	s_cmp_eq_u32 s40, 0
	s_cbranch_scc1 .LmB_bar2
	s_add_i32 s41, s39, 0xffffff81
	s_cmp_le_i32 s41, s75
	s_cbranch_scc0 .LmB_bar2
	s_waitcnt lgkmcnt(8)
	v_mfma_f32_32x32x16_bf16 v[64:79], v[168:171], v[100:103], v[64:79]
	ds_read_b64_tr_b16 v[144:145], v0 offset:0x3000
	ds_read_b64_tr_b16 v[146:147], v0 offset:0x3100
	ds_read_b64_tr_b16 v[140:141], v0 offset:0x3200
	ds_read_b64_tr_b16 v[142:143], v0 offset:0x3300
	ds_read_b64_tr_b16 v[136:137], v0 offset:0x3400
	ds_read_b64_tr_b16 v[138:139], v0 offset:0x3500
	ds_read_b64_tr_b16 v[132:133], v0 offset:0x3600
	ds_read_b64_tr_b16 v[134:135], v0 offset:0x3700
	v_mfma_f32_32x32x16_bf16 v[48:63], v[10:13], v[100:103], v[48:63]
	v_mfma_f32_32x32x16_bf16 v[32:47], v[180:183], v[100:103], v[32:47]
	v_mfma_f32_32x32x16_bf16 v[16:31], v[2:5], v[100:103], v[16:31]
	v_cvt_pk_bf16_f32 v80, v200, v201
	v_cvt_pk_bf16_f32 v81, v202, v203
	v_cvt_pk_bf16_f32 v82, v204, v205
	v_add_f32_e32 v14, v242, v14
	v_cvt_pk_bf16_f32 v83, v206, v207
	v_add_f32_e32 v14, v243, v14
	s_waitcnt lgkmcnt(8)
	v_mfma_f32_32x32x16_bf16 v[64:79], v[6:9], v[80:83], v[64:79]
	v_exp_f32_e32 v2, v88
	v_exp_f32_e32 v3, v89
	v_exp_f32_e32 v4, v90
	v_mfma_f32_32x32x16_bf16 v[48:63], v[128:131], v[80:83], v[48:63]
	v_exp_f32_e32 v5, v91
	v_exp_f32_e32 v10, v92
	v_exp_f32_e32 v11, v93
	v_mfma_f32_32x32x16_bf16 v[32:47], v[172:175], v[80:83], v[32:47]
	v_exp_f32_e32 v12, v94
	v_exp_f32_e32 v13, v95
	v_add_f32_e32 v14, v244, v14
	v_add_f32_e32 v14, v245, v14
	v_mfma_f32_32x32x16_bf16 v[16:31], v[184:187], v[80:83], v[16:31]
	v_cvt_pk_bf16_f32 v84, v2, v3
	v_cvt_pk_bf16_f32 v85, v4, v5
	v_cvt_pk_bf16_f32 v86, v10, v11
	v_add_f32_e32 v14, v246, v14
	v_cvt_pk_bf16_f32 v87, v12, v13
	v_add_f32_e32 v14, v247, v14
	v_add_f32_e32 v14, v248, v14
	s_waitcnt lgkmcnt(0)
	v_add_f32_e32 v14, v249, v14
	v_add_f32_e32 v14, v250, v14
	v_add_f32_e32 v14, v251, v14
	v_add_f32_e32 v14, v252, v14
	v_add_f32_e32 v14, v253, v14
	v_mfma_f32_32x32x16_bf16 v[64:79], v[144:147], v[84:87], v[64:79]
	v_add_f32_e32 v14, v200, v14
	v_add_f32_e32 v14, v201, v14
	v_add_f32_e32 v14, v202, v14
	v_add_f32_e32 v14, v203, v14
	v_add_f32_e32 v14, v204, v14
	v_add_f32_e32 v14, v205, v14
	v_mfma_f32_32x32x16_bf16 v[48:63], v[140:143], v[84:87], v[48:63]
	v_add_f32_e32 v14, v206, v14
	v_add_f32_e32 v14, v207, v14
	v_add_f32_e32 v14, v2, v14
	v_add_f32_e32 v14, v3, v14
	v_add_f32_e32 v14, v4, v14
	v_add_f32_e32 v14, v5, v14
	v_mfma_f32_32x32x16_bf16 v[32:47], v[136:139], v[84:87], v[32:47]
	v_add_f32_e32 v14, v10, v14
	v_add_f32_e32 v14, v11, v14
	v_add_f32_e32 v14, v12, v14
	v_add_f32_e32 v14, v13, v14
	v_add_f32_e32 v163, v163, v14
	v_mfma_f32_32x32x16_bf16 v[16:31], v[132:135], v[84:87], v[16:31]


; #define ATT_PV(v_, p_) do { const bf16x8 pf_ = __builtin_bit_cast(bf16x8, (p_)); _Pragma("unroll") for (int d = 0; d < 4; ++d) { \
;         const bf16x8 vf_ = __builtin_shufflevector((v_)[2 * d], (v_)[2 * d + 1], 0, 1, 2, 3, 4, 5, 6, 7); O[d] = MFMA32(vf_, pf_, O[d]); } } while (0)
; template <bool ONLINE, int NO>
; __device__ __forceinline__ void softmax_tile(f32x16 (&s)[2], float& m, float& l, f32x16 (&O)[NO], u32x4 (&pk)[4]) {
;     ...
;     float ps = 0.f;
; #pragma unroll
;     for (int blk = 0; blk < 2; ++blk)
; #pragma unroll
;         for (int i = 0; i < 16; ++i) { const float p = __builtin_amdgcn_exp2f(ONLINE ? (s[blk][i] - mn) : s[blk][i]); ps += p; s[blk][i] = p; }
;     l += ps;
; #pragma unroll
;     for (int blk = 0; blk < 2; ++blk)
; #pragma unroll
;         for (int sh = 0; sh < 2; ++sh) { u32x4 pw;
;             pw.x = cvt_pk_bf16(s[blk][8 * sh], s[blk][8 * sh + 1]); pw.y = cvt_pk_bf16(s[blk][8 * sh + 2], s[blk][8 * sh + 3]);
;             pw.z = cvt_pk_bf16(s[blk][8 * sh + 4], s[blk][8 * sh + 5]); pw.w = cvt_pk_bf16(s[blk][8 * sh + 6], s[blk][8 * sh + 7]); pk[2 * blk + sh] = pw; }
; template <int MODE>
; __device__ __forceinline__ void attn_unit(const Params& P, LAS unsigned char* lds, const int b, const int h, const int qb) {
;     ...
;             softmax_tile<ONLINE, 4>(s, m1, l1, O, pk1);
;             if constexpr (MODE == 1) {
;                 v_issue<2>(vc, vaddr); v_wait<15>(va); ATT_PV(va, pk1[0]); v_issue<3>(vd, vaddr); v_wait<15>(vb); ATT_PV(vb, pk1[1]); v_wait<8>(vc); ATT_PV(vc, pk1[2]); v_wait<0>(vd); ATT_PV(vd, pk1[3]);
.Lm1_fast:
	s_cmpk_lt_u32 s58, 0x100
	s_cbranch_scc0 .Lm1_fastB
	v_mfma_f32_32x32x16_bf16 v[96:111], v[2:5], v[112:115], 0
	v_mfma_f32_32x32x16_bf16 v[96:111], v[10:13], v[116:119], v[96:111]
	v_mfma_f32_32x32x16_bf16 v[96:111], v[168:171], v[120:123], v[96:111]
	v_mfma_f32_32x32x16_bf16 v[96:111], v[180:183], v[124:127], v[96:111]
	ds_read_b64_tr_b16 v[168:169], v0 offset:0x1000
	ds_read_b64_tr_b16 v[170:171], v0 offset:0x1100
	ds_read_b64_tr_b16 v[10:11], v0 offset:0x1200
	ds_read_b64_tr_b16 v[12:13], v0 offset:0x1300
	ds_read_b64_tr_b16 v[180:181], v0 offset:0x1400
	ds_read_b64_tr_b16 v[182:183], v0 offset:0x1500
	ds_read_b64_tr_b16 v[2:3], v0 offset:0x1600
	ds_read_b64_tr_b16 v[4:5], v0 offset:0x1700
	v_mfma_f32_32x32x16_bf16 v[80:95], v[6:9], v[112:115], 0
	s_nop 2
	v_exp_f32_e32 v14, v96
	v_exp_f32_e32 v15, v97
	v_mfma_f32_32x32x16_bf16 v[80:95], v[128:131], v[116:119], v[80:95]
	v_exp_f32_e32 v240, v98
	v_exp_f32_e32 v241, v99
	v_exp_f32_e32 v242, v100
	v_mfma_f32_32x32x16_bf16 v[80:95], v[172:175], v[120:123], v[80:95]
	v_exp_f32_e32 v243, v101
	v_exp_f32_e32 v244, v102
	v_exp_f32_e32 v245, v103
	v_mfma_f32_32x32x16_bf16 v[80:95], v[184:187], v[124:127], v[80:95]
	v_cvt_pk_bf16_f32 v96, v14, v15
	v_cvt_pk_bf16_f32 v97, v240, v241
	v_cvt_pk_bf16_f32 v98, v242, v243
	v_cvt_pk_bf16_f32 v99, v244, v245
	v_exp_f32_e32 v246, v104
	s_waitcnt lgkmcnt(8)
	v_mfma_f32_32x32x16_bf16 v[64:79], v[144:147], v[96:99], v[64:79]
	ds_read_b64_tr_b16 v[6:7], v0 offset:0x2000
	ds_read_b64_tr_b16 v[8:9], v0 offset:0x2100
	ds_read_b64_tr_b16 v[128:129], v0 offset:0x2200
	ds_read_b64_tr_b16 v[130:131], v0 offset:0x2300
	ds_read_b64_tr_b16 v[172:173], v0 offset:0x2400
	ds_read_b64_tr_b16 v[174:175], v0 offset:0x2500
	ds_read_b64_tr_b16 v[184:185], v0 offset:0x2600
	ds_read_b64_tr_b16 v[186:187], v0 offset:0x2700
	v_mfma_f32_32x32x16_bf16 v[48:63], v[140:143], v[96:99], v[48:63]
	v_exp_f32_e32 v247, v105
	v_exp_f32_e32 v248, v106
	v_exp_f32_e32 v249, v107
	v_exp_f32_e32 v200, v80
	v_exp_f32_e32 v201, v81
	v_mfma_f32_32x32x16_bf16 v[32:47], v[136:139], v[96:99], v[32:47]
	v_exp_f32_e32 v250, v108
	v_exp_f32_e32 v251, v109
	v_exp_f32_e32 v252, v110
	v_exp_f32_e32 v202, v82
	v_exp_f32_e32 v203, v83
	v_exp_f32_e32 v204, v84
	v_mfma_f32_32x32x16_bf16 v[16:31], v[132:135], v[96:99], v[16:31]
	v_exp_f32_e32 v253, v111
	v_exp_f32_e32 v205, v85
	v_exp_f32_e32 v206, v86
	v_exp_f32_e32 v207, v87
	v_add_f32_e32 v14, v15, v14
	v_cvt_pk_bf16_f32 v100, v246, v247
	v_cvt_pk_bf16_f32 v101, v248, v249
	v_cvt_pk_bf16_f32 v102, v250, v251
	v_add_f32_e32 v14, v240, v14
	v_cvt_pk_bf16_f32 v103, v252, v253
	v_add_f32_e32 v14, v241, v14
	s_barrier
	s_waitcnt lgkmcnt(8)
	v_mfma_f32_32x32x16_bf16 v[64:79], v[168:171], v[100:103], v[64:79]
	ds_read_b64_tr_b16 v[144:145], v0 offset:0x3000
	ds_read_b64_tr_b16 v[146:147], v0 offset:0x3100
	ds_read_b64_tr_b16 v[140:141], v0 offset:0x3200
	ds_read_b64_tr_b16 v[142:143], v0 offset:0x3300
	ds_read_b64_tr_b16 v[136:137], v0 offset:0x3400
	ds_read_b64_tr_b16 v[138:139], v0 offset:0x3500
	ds_read_b64_tr_b16 v[132:133], v0 offset:0x3600
	ds_read_b64_tr_b16 v[134:135], v0 offset:0x3700
	v_mfma_f32_32x32x16_bf16 v[48:63], v[10:13], v[100:103], v[48:63]
	v_mfma_f32_32x32x16_bf16 v[32:47], v[180:183], v[100:103], v[32:47]
	v_mfma_f32_32x32x16_bf16 v[16:31], v[2:5], v[100:103], v[16:31]
	v_cvt_pk_bf16_f32 v80, v200, v201
	v_cvt_pk_bf16_f32 v81, v202, v203
	v_cvt_pk_bf16_f32 v82, v204, v205
	v_add_f32_e32 v14, v242, v14
	v_cvt_pk_bf16_f32 v83, v206, v207
	v_add_f32_e32 v14, v243, v14
	s_waitcnt lgkmcnt(8)
	v_mfma_f32_32x32x16_bf16 v[64:79], v[6:9], v[80:83], v[64:79]
	v_exp_f32_e32 v2, v88
	v_exp_f32_e32 v3, v89
	v_exp_f32_e32 v4, v90
	v_mfma_f32_32x32x16_bf16 v[48:63], v[128:131], v[80:83], v[48:63]
	v_exp_f32_e32 v5, v91
	v_exp_f32_e32 v10, v92
	v_exp_f32_e32 v11, v93
	v_mfma_f32_32x32x16_bf16 v[32:47], v[172:175], v[80:83], v[32:47]
	v_exp_f32_e32 v12, v94
	v_exp_f32_e32 v13, v95
	v_add_f32_e32 v14, v244, v14
	v_add_f32_e32 v14, v245, v14
	v_mfma_f32_32x32x16_bf16 v[16:31], v[184:187], v[80:83], v[16:31]
	v_cvt_pk_bf16_f32 v84, v2, v3
	v_cvt_pk_bf16_f32 v85, v4, v5
	v_cvt_pk_bf16_f32 v86, v10, v11
	v_add_f32_e32 v14, v246, v14
	v_cvt_pk_bf16_f32 v87, v12, v13
	v_add_f32_e32 v14, v247, v14
	v_add_f32_e32 v14, v248, v14
	s_waitcnt lgkmcnt(0)
	v_add_f32_e32 v14, v249, v14
	v_add_f32_e32 v14, v250, v14
	v_add_f32_e32 v14, v251, v14
	v_add_f32_e32 v14, v252, v14
	v_add_f32_e32 v14, v253, v14
	s_add_i32 s41, s40, 3
	s_cmp_ge_u32 s41, s22
	s_cbranch_scc1 .Lm1f_nodma
	s_cmpk_gt_u32 s58, 0xff
	s_cbranch_scc1 .Lm1f_nodma
	v_mfma_f32_32x32x16_bf16 v[64:79], v[144:147], v[84:87], v[64:79]
	s_mov_b64 s[70:71], 0x1000
	s_add_i32 s41, s38, 0x18000
	s_and_b32 s41, s41, 0x18000
	s_add_i32 s41, s77, s41
	v_lshl_add_u64 v[240:241], v[152:153], 0, s[68:69]
	v_lshl_add_u64 v[242:243], v[240:241], 0, s[42:43]
	s_mov_b32 m0, s41
	v_lshl_add_u64 v[240:241], v[240:241], 0, s[44:45]
	global_load_lds_dwordx4 v[242:243], off
	v_mfma_f32_32x32x16_bf16 v[48:63], v[140:143], v[84:87], v[48:63]
	s_add_i32 m0, s41, 0x1000
	v_lshl_add_u64 v[242:243], v[242:243], 0, s[70:71]
	global_load_lds_dwordx4 v[242:243], off
	s_add_i32 m0, s41, 0x2000
	v_lshl_add_u64 v[242:243], v[240:241], 0, s[70:71]
	global_load_lds_dwordx4 v[240:241], off
	s_add_i32 m0, s41, 0x3000
	v_lshl_add_u64 v[240:241], v[154:155], 0, s[68:69]
	global_load_lds_dwordx4 v[242:243], off
	v_add_f32_e32 v14, v200, v14
	v_add_f32_e32 v14, v201, v14
	v_add_f32_e32 v14, v202, v14
	v_add_f32_e32 v14, v203, v14
	v_mfma_f32_32x32x16_bf16 v[32:47], v[136:139], v[84:87], v[32:47]
	v_lshl_add_u64 v[242:243], v[240:241], 0, s[48:49]
	s_add_i32 m0, s41, 0x4000
	v_lshl_add_u64 v[240:241], v[240:241], 0, s[50:51]
	global_load_lds_dwordx4 v[242:243], off
	s_add_i32 m0, s41, 0x5000
	v_lshl_add_u64 v[242:243], v[242:243], 0, s[70:71]
	global_load_lds_dwordx4 v[242:243], off
	v_add_f32_e32 v14, v204, v14
	v_add_f32_e32 v14, v205, v14
	v_add_f32_e32 v14, v206, v14
	v_add_f32_e32 v14, v207, v14
	v_add_f32_e32 v14, v2, v14
	v_add_f32_e32 v14, v3, v14
	v_mfma_f32_32x32x16_bf16 v[16:31], v[132:135], v[84:87], v[16:31]
	s_add_i32 m0, s41, 0x6000
	v_lshl_add_u64 v[242:243], v[240:241], 0, s[70:71]
	global_load_lds_dwordx4 v[240:241], off
	s_add_i32 m0, s41, 0x7000
	s_nop 0
	global_load_lds_dwordx4 v[242:243], off
	v_add_f32_e32 v14, v4, v14
	v_add_f32_e32 v14, v5, v14
	v_add_f32_e32 v14, v10, v14
	v_add_f32_e32 v14, v11, v14
	v_add_f32_e32 v14, v12, v14
	v_add_f32_e32 v14, v13, v14
	v_add_f32_e32 v163, v163, v14
	s_branch .LBB0_474
; #define ATT_PV(v_, p_) do { const bf16x8 pf_ = __builtin_bit_cast(bf16x8, (p_)); _Pragma("unroll") for (int d = 0; d < 4; ++d) { \
;         const bf16x8 vf_ = __builtin_shufflevector((v_)[2 * d], (v_)[2 * d + 1], 0, 1, 2, 3, 4, 5, 6, 7); O[d] = MFMA32(vf_, pf_, O[d]); } } while (0)
; template <bool ONLINE, int NO>
; __device__ __forceinline__ void softmax_tile(f32x16 (&s)[2], float& m, float& l, f32x16 (&O)[NO], u32x4 (&pk)[4]) {
;     ...
;     float ps = 0.f;
; #pragma unroll
;     for (int blk = 0; blk < 2; ++blk)
; #pragma unroll
;         for (int i = 0; i < 16; ++i) { const float p = __builtin_amdgcn_exp2f(ONLINE ? (s[blk][i] - mn) : s[blk][i]); ps += p; s[blk][i] = p; }
;     l += ps;
; template <int MODE>
; __device__ __forceinline__ void attn_unit(const Params& P, LAS unsigned char* lds, const int b, const int h, const int qb) {
;     ...
;             softmax_tile<ONLINE, 4>(s, m1, l1, O, pk1);
;             if constexpr (MODE == 1) {
;                 v_issue<2>(vc, vaddr); v_wait<15>(va); ATT_PV(va, pk1[0]); v_issue<3>(vd, vaddr); v_wait<15>(vb); ATT_PV(vb, pk1[1]); v_wait<8>(vc); ATT_PV(vc, pk1[2]); v_wait<0>(vd); ATT_PV(vd, pk1[3]);
.Lm1f_nodma:
	v_mfma_f32_32x32x16_bf16 v[64:79], v[144:147], v[84:87], v[64:79]
	v_add_f32_e32 v14, v200, v14
	v_add_f32_e32 v14, v201, v14
	v_add_f32_e32 v14, v202, v14
	v_add_f32_e32 v14, v203, v14
	v_add_f32_e32 v14, v204, v14
	v_add_f32_e32 v14, v205, v14
	v_mfma_f32_32x32x16_bf16 v[48:63], v[140:143], v[84:87], v[48:63]
	v_add_f32_e32 v14, v206, v14
	v_add_f32_e32 v14, v207, v14
	v_add_f32_e32 v14, v2, v14
	v_add_f32_e32 v14, v3, v14
	v_add_f32_e32 v14, v4, v14
	v_add_f32_e32 v14, v5, v14
	v_mfma_f32_32x32x16_bf16 v[32:47], v[136:139], v[84:87], v[32:47]
	v_add_f32_e32 v14, v10, v14
	v_add_f32_e32 v14, v11, v14
	v_add_f32_e32 v14, v12, v14
	v_add_f32_e32 v14, v13, v14
	v_add_f32_e32 v163, v163, v14
	v_mfma_f32_32x32x16_bf16 v[16:31], v[132:135], v[84:87], v[16:31]
	s_branch .LBB0_474

; #define ATT_PV(v_, p_) do { const bf16x8 pf_ = __builtin_bit_cast(bf16x8, (p_)); _Pragma("unroll") for (int d = 0; d < 4; ++d) { \
;         const bf16x8 vf_ = __builtin_shufflevector((v_)[2 * d], (v_)[2 * d + 1], 0, 1, 2, 3, 4, 5, 6, 7); O[d] = MFMA32(vf_, pf_, O[d]); } } while (0)
; template <bool ONLINE, int NO>
; __device__ __forceinline__ void softmax_tile(f32x16 (&s)[2], float& m, float& l, f32x16 (&O)[NO], u32x4 (&pk)[4]) {
;     ...
;     float ps = 0.f;
; #pragma unroll
;     for (int blk = 0; blk < 2; ++blk)
; #pragma unroll
;         for (int i = 0; i < 16; ++i) { const float p = __builtin_amdgcn_exp2f(ONLINE ? (s[blk][i] - mn) : s[blk][i]); ps += p; s[blk][i] = p; }
;     l += ps;
; #pragma unroll
;     for (int blk = 0; blk < 2; ++blk)
; #pragma unroll
;         for (int sh = 0; sh < 2; ++sh) { u32x4 pw;
;             pw.x = cvt_pk_bf16(s[blk][8 * sh], s[blk][8 * sh + 1]); pw.y = cvt_pk_bf16(s[blk][8 * sh + 2], s[blk][8 * sh + 3]);
;             pw.z = cvt_pk_bf16(s[blk][8 * sh + 4], s[blk][8 * sh + 5]); pw.w = cvt_pk_bf16(s[blk][8 * sh + 6], s[blk][8 * sh + 7]); pk[2 * blk + sh] = pw; }
; template <int MODE>
; __device__ __forceinline__ void attn_unit(const Params& P, LAS unsigned char* lds, const int b, const int h, const int qb) {
;     ...
;             softmax_tile<ONLINE, 4>(s, m1, l1, O, pk1);
;             if constexpr (MODE == 1) {
;                 v_issue<2>(vc, vaddr); v_wait<15>(va); ATT_PV(va, pk1[0]); v_issue<3>(vd, vaddr); v_wait<15>(vb); ATT_PV(vb, pk1[1]); v_wait<8>(vc); ATT_PV(vc, pk1[2]); v_wait<0>(vd); ATT_PV(vd, pk1[3]);
.Lm1_fastB:
	v_mfma_f32_32x32x16_bf16 v[96:111], v[2:5], v[112:115], 0
	v_mfma_f32_32x32x16_bf16 v[96:111], v[10:13], v[116:119], v[96:111]
	v_mfma_f32_32x32x16_bf16 v[96:111], v[168:171], v[120:123], v[96:111]
	v_mfma_f32_32x32x16_bf16 v[96:111], v[180:183], v[124:127], v[96:111]
	ds_read_b64_tr_b16 v[168:169], v0 offset:0x1000
	ds_read_b64_tr_b16 v[170:171], v0 offset:0x1100
	ds_read_b64_tr_b16 v[10:11], v0 offset:0x1200
	ds_read_b64_tr_b16 v[12:13], v0 offset:0x1300
	ds_read_b64_tr_b16 v[180:181], v0 offset:0x1400
	ds_read_b64_tr_b16 v[182:183], v0 offset:0x1500
	ds_read_b64_tr_b16 v[2:3], v0 offset:0x1600
	ds_read_b64_tr_b16 v[4:5], v0 offset:0x1700
	v_mfma_f32_32x32x16_bf16 v[80:95], v[6:9], v[112:115], 0
	s_nop 2
	v_exp_f32_e32 v14, v96
	v_exp_f32_e32 v15, v97
	v_mfma_f32_32x32x16_bf16 v[80:95], v[128:131], v[116:119], v[80:95]
	v_exp_f32_e32 v240, v98
	v_exp_f32_e32 v241, v99
	v_exp_f32_e32 v242, v100
	v_mfma_f32_32x32x16_bf16 v[80:95], v[172:175], v[120:123], v[80:95]
	v_exp_f32_e32 v243, v101
	v_exp_f32_e32 v244, v102
	v_exp_f32_e32 v245, v103
	v_mfma_f32_32x32x16_bf16 v[80:95], v[184:187], v[124:127], v[80:95]
	v_cvt_pk_bf16_f32 v96, v14, v15
	v_cvt_pk_bf16_f32 v97, v240, v241
	v_cvt_pk_bf16_f32 v98, v242, v243
	v_cvt_pk_bf16_f32 v99, v244, v245
	v_exp_f32_e32 v246, v104
	s_waitcnt lgkmcnt(8)
	v_mfma_f32_32x32x16_bf16 v[64:79], v[144:147], v[96:99], v[64:79]
	ds_read_b64_tr_b16 v[6:7], v0 offset:0x2000
	ds_read_b64_tr_b16 v[8:9], v0 offset:0x2100
	ds_read_b64_tr_b16 v[128:129], v0 offset:0x2200
	ds_read_b64_tr_b16 v[130:131], v0 offset:0x2300
	ds_read_b64_tr_b16 v[172:173], v0 offset:0x2400
	ds_read_b64_tr_b16 v[174:175], v0 offset:0x2500
	ds_read_b64_tr_b16 v[184:185], v0 offset:0x2600
	ds_read_b64_tr_b16 v[186:187], v0 offset:0x2700
	v_mfma_f32_32x32x16_bf16 v[48:63], v[140:143], v[96:99], v[48:63]
	v_exp_f32_e32 v247, v105
	v_exp_f32_e32 v248, v106
	v_exp_f32_e32 v249, v107
	v_exp_f32_e32 v200, v80
	v_exp_f32_e32 v201, v81
	v_mfma_f32_32x32x16_bf16 v[32:47], v[136:139], v[96:99], v[32:47]
	v_exp_f32_e32 v250, v108
	v_exp_f32_e32 v251, v109
	v_exp_f32_e32 v252, v110
	v_exp_f32_e32 v202, v82
	v_exp_f32_e32 v203, v83
	v_exp_f32_e32 v204, v84
	v_mfma_f32_32x32x16_bf16 v[16:31], v[132:135], v[96:99], v[16:31]
	v_exp_f32_e32 v253, v111
	v_exp_f32_e32 v205, v85
	v_exp_f32_e32 v206, v86
	v_exp_f32_e32 v207, v87
	v_add_f32_e32 v14, v15, v14
	v_cvt_pk_bf16_f32 v100, v246, v247
	v_cvt_pk_bf16_f32 v101, v248, v249
	v_cvt_pk_bf16_f32 v102, v250, v251
	v_add_f32_e32 v14, v240, v14
	v_cvt_pk_bf16_f32 v103, v252, v253
	v_add_f32_e32 v14, v241, v14
	s_branch .LBB0_474
